# rstd_prologue: replace per-unit generic integer-division tile mapping (50 SALU + rcp + readfirstlane) by closed form pm=(L&7)*8+((L>>3)&7), 21 units, on top of v22
# baseline (speedup 1.0000x reference)
;     __device__ bool next(int i, Unit& u) const { Unit b; if (!so.next(i >> 2, b)) return false; const int sub = i & 3; u.pm = b.pm; u.pn = sub * 4 + b.pn; u.acol = sub * 512; u.ord = i; return true; }
;     __device__ bool next(int i, Unit& u) const {
;         const long L = (long)i * G + c; if (L >= nwg) return false;
;         int wgid = (int)L; { const int q = nwg / NXCD, r = nwg % NXCD, xcd = wgid % NXCD, off = wgid / NXCD; wgid = (xcd < r ? xcd * (q + 1) : r * (q + 1) + (xcd - r) * q) + off; }
;         const int nig = WGM * nN, gid = wgid / nig, fm = gid * WGM, gsz = (nM - fm) < WGM ? (nM - fm) : WGM;
;         u.pm = fm + ((wgid % nig) % gsz); u.pn = (wgid % nig) / gsz; u.acol = 0; u.ord = i; return true;
; __device__ __forceinline__ float row_rstd(const float* rowsq, size_t row) {
;     const f32x4* q = (const f32x4*)(rowsq + row * 16); const f32x4 a = q[0], b = q[1], c = q[2], d = q[3];
.LBB0_186:
	s_ashr_i32 s34, s94, 31
	s_ashr_i32 s48, s71, 31
	s_cmpk_lt_i32 s71, 0x580
	v_mov_b32_e32 v2, v216
	s_cselect_b64 s[24:25], -1, 0
	s_cmpk_gt_i32 s71, 0x57f
	s_cbranch_scc1 .LBB0_222
	v_readlane_b32 s2, v253, 37
	v_ashrrev_i32_e32 v3, 31, v2
	v_readlane_b32 s26, v251, 40
	v_lshl_add_u32 v0, v2, 2, s2
	v_cmp_gt_i32_e64 s[2:3], s91, v2
	v_lshlrev_b64 v[2:3], 6, v[2:3]
	v_readlane_b32 s27, v251, 41
	s_nop 1
	v_lshl_add_u64 v[2:3], s[26:27], 0, v[2:3]
	s_and_saveexec_b64 s[26:27], s[2:3]
	s_cbranch_execz .LBB0_189
	s_and_b32 s28, s71, 7
	s_lshl_b32 s28, s28, 3
	s_bfe_u32 s29, s71, 0x30003
	s_or_b32 s28, s28, s29
	s_mov_b32 s29, 0
	s_lshl_b64 s[28:29], s[28:29], 14
	v_lshl_add_u64 v[36:37], v[2:3], 0, s[28:29]
	global_load_dwordx4 v[24:27], v[36:37], off
	global_load_dwordx4 v[28:31], v[36:37], off offset:16
	global_load_dwordx4 v[32:35], v[36:37], off offset:32
	s_nop 0
	global_load_dwordx4 v[36:39], v[36:37], off offset:48
.LBB0_189:
	s_or_b64 exec, exec, s[26:27]
	s_add_u32 s26, s94, s71
	s_addc_u32 s27, s34, s48
	v_cmp_gt_i64_e32 vcc, s[26:27], v[184:185]
	s_cbranch_vccnz .Lmy_rsa_0_c1
	s_and_saveexec_b64 s[28:29], s[2:3]
	s_cbranch_execz .LBB0_192
	s_and_b32 s30, s26, 7
	s_lshl_b32 s30, s30, 3
	s_bfe_u32 s31, s26, 0x30003
	s_or_b32 s30, s30, s31
	s_mov_b32 s31, 0
	s_lshl_b64 s[30:31], s[30:31], 14
	v_lshl_add_u64 v[52:53], v[2:3], 0, s[30:31]
	global_load_dwordx4 v[40:43], v[52:53], off
	global_load_dwordx4 v[44:47], v[52:53], off offset:16
	global_load_dwordx4 v[48:51], v[52:53], off offset:32
	s_nop 0
	global_load_dwordx4 v[52:55], v[52:53], off offset:48
.LBB0_192:
	s_or_b64 exec, exec, s[28:29]
	s_add_u32 s26, s26, s94
	s_addc_u32 s27, s27, s34
	v_cmp_gt_i64_e32 vcc, s[26:27], v[184:185]
	s_cbranch_vccnz .Lmy_rsa_0_c2
	s_and_saveexec_b64 s[28:29], s[2:3]
	s_cbranch_execz .LBB0_195
	s_and_b32 s30, s26, 7
	s_lshl_b32 s30, s30, 3
	s_bfe_u32 s31, s26, 0x30003
	s_or_b32 s30, s30, s31
	s_mov_b32 s31, 0
	s_lshl_b64 s[30:31], s[30:31], 14
	v_lshl_add_u64 v[68:69], v[2:3], 0, s[30:31]
	global_load_dwordx4 v[56:59], v[68:69], off
	global_load_dwordx4 v[60:63], v[68:69], off offset:16
	global_load_dwordx4 v[64:67], v[68:69], off offset:32
	s_nop 0
	global_load_dwordx4 v[68:71], v[68:69], off offset:48
.LBB0_195:
	s_or_b64 exec, exec, s[28:29]
	s_add_u32 s26, s26, s94
	s_addc_u32 s27, s27, s34
	v_cmp_gt_i64_e32 vcc, s[26:27], v[184:185]
	s_cbranch_vccnz .Lmy_rsa_0_c3
	s_and_saveexec_b64 s[28:29], s[2:3]
	s_cbranch_execz .LBB0_198
	s_and_b32 s30, s26, 7
	s_lshl_b32 s30, s30, 3
	s_bfe_u32 s31, s26, 0x30003
	s_or_b32 s30, s30, s31
	s_mov_b32 s31, 0
	s_lshl_b64 s[30:31], s[30:31], 14
	v_lshl_add_u64 v[84:85], v[2:3], 0, s[30:31]
	global_load_dwordx4 v[72:75], v[84:85], off
	global_load_dwordx4 v[76:79], v[84:85], off offset:16
	global_load_dwordx4 v[80:83], v[84:85], off offset:32
	s_nop 0
	global_load_dwordx4 v[84:87], v[84:85], off offset:48
.LBB0_198:
	s_or_b64 exec, exec, s[28:29]
	s_add_u32 s26, s26, s94
	s_addc_u32 s27, s27, s34
	v_cmp_gt_i64_e32 vcc, s[26:27], v[184:185]
	s_cbranch_vccnz .Lmy_rsa_0_c4
	s_and_saveexec_b64 s[28:29], s[2:3]
	s_cbranch_execz .LBB0_201
	s_and_b32 s30, s26, 7
	s_lshl_b32 s30, s30, 3
	s_bfe_u32 s31, s26, 0x30003
	s_or_b32 s30, s30, s31
	s_mov_b32 s31, 0
	s_lshl_b64 s[30:31], s[30:31], 14
	v_lshl_add_u64 v[100:101], v[2:3], 0, s[30:31]
	global_load_dwordx4 v[88:91], v[100:101], off
	global_load_dwordx4 v[92:95], v[100:101], off offset:16
	global_load_dwordx4 v[96:99], v[100:101], off offset:32
	s_nop 0
	global_load_dwordx4 v[100:103], v[100:101], off offset:48
.LBB0_201:
	s_or_b64 exec, exec, s[28:29]
	s_add_u32 s26, s26, s94
	s_addc_u32 s27, s27, s34
	v_cmp_gt_i64_e32 vcc, s[26:27], v[184:185]
	s_cbranch_vccnz .Lmy_rsa_0_c5
	s_and_saveexec_b64 s[28:29], s[2:3]
	s_cbranch_execz .LBB0_204
	s_and_b32 s30, s26, 7
	s_lshl_b32 s30, s30, 3
	s_bfe_u32 s31, s26, 0x30003
	s_or_b32 s30, s30, s31
	s_mov_b32 s31, 0
	s_lshl_b64 s[30:31], s[30:31], 14
	v_lshl_add_u64 v[116:117], v[2:3], 0, s[30:31]
	global_load_dwordx4 v[104:107], v[116:117], off
	global_load_dwordx4 v[108:111], v[116:117], off offset:16
	global_load_dwordx4 v[112:115], v[116:117], off offset:32
	s_nop 0
	global_load_dwordx4 v[116:119], v[116:117], off offset:48
	s_or_b64 exec, exec, s[28:29]

;     __device__ bool next(int i, Unit& u) const { Unit b; if (!so.next(i >> 2, b)) return false; const int sub = i & 3; u.pm = b.pm; u.pn = sub * 4 + b.pn; u.acol = sub * 512; u.ord = i; return true; }
;     __device__ bool next(int i, Unit& u) const {
;         const long L = (long)i * G + c; if (L >= nwg) return false;
;         int wgid = (int)L; { const int q = nwg / NXCD, r = nwg % NXCD, xcd = wgid % NXCD, off = wgid / NXCD; wgid = (xcd < r ? xcd * (q + 1) : r * (q + 1) + (xcd - r) * q) + off; }
;         const int nig = WGM * nN, gid = wgid / nig, fm = gid * WGM, gsz = (nM - fm) < WGM ? (nM - fm) : WGM;
;         u.pm = fm + ((wgid % nig) % gsz); u.pn = (wgid % nig) / gsz; u.acol = 0; u.ord = i; return true;
; __device__ __forceinline__ float row_rstd(const float* rowsq, size_t row) {
;     const f32x4* q = (const f32x4*)(rowsq + row * 16); const f32x4 a = q[0], b = q[1], c = q[2], d = q[3];
.LBB0_388:
	s_or_b64 exec, exec, s[0:1]
	v_readlane_b32 s0, v254, 5
	s_waitcnt lgkmcnt(0)
	s_barrier
	v_readlane_b32 s1, v254, 6
	s_ashr_i32 s34, s94, 31
	s_ashr_i32 s48, s71, 31
	v_writelane_b32 v254, s0, 5
	s_cmpk_lt_i32 s71, 0x900
	v_mov_b32_e32 v2, v216
	v_writelane_b32 v254, s1, 6
	s_cselect_b64 s[0:1], -1, 0
	s_cmpk_gt_i32 s71, 0x8ff
	s_cbranch_scc1 .LBB0_424
	v_readlane_b32 s2, v253, 37
	v_ashrrev_i32_e32 v3, 31, v2
	v_cmp_gt_i32_e64 s[36:37], s91, v2
	v_lshl_add_u32 v0, v2, 2, s2
	v_readlane_b32 s2, v251, 42
	v_lshlrev_b64 v[2:3], 6, v[2:3]
	v_readlane_b32 s3, v251, 43
	s_nop 1
	v_lshl_add_u64 v[2:3], s[2:3], 0, v[2:3]
	s_and_saveexec_b64 s[2:3], s[36:37]
	s_cbranch_execz .LBB0_391
	s_and_b32 s24, s71, 7
	s_lshl_b32 s24, s24, 3
	s_bfe_u32 s25, s71, 0x30003
	s_or_b32 s24, s24, s25
	s_mov_b32 s25, 0
	s_lshl_b64 s[24:25], s[24:25], 14
	v_lshl_add_u64 v[36:37], v[2:3], 0, s[24:25]
	global_load_dwordx4 v[24:27], v[36:37], off offset:48
	global_load_dwordx4 v[28:31], v[36:37], off offset:32
	global_load_dwordx4 v[32:35], v[36:37], off offset:16
	s_nop 0
	global_load_dwordx4 v[36:39], v[36:37], off
.LBB0_391:
	s_or_b64 exec, exec, s[2:3]
	s_add_u32 s2, s94, s71
	s_addc_u32 s3, s34, s48
	v_cmp_gt_i64_e32 vcc, s[2:3], v[192:193]
	s_cbranch_vccnz .Lmy_rsb_0_c1
	s_and_saveexec_b64 s[24:25], s[36:37]
	s_cbranch_execz .LBB0_394
	s_and_b32 s26, s2, 7
	s_lshl_b32 s26, s26, 3
	s_bfe_u32 s27, s2, 0x30003
	s_or_b32 s26, s26, s27
	s_mov_b32 s27, 0
	s_lshl_b64 s[26:27], s[26:27], 14
	v_lshl_add_u64 v[52:53], v[2:3], 0, s[26:27]
	global_load_dwordx4 v[40:43], v[52:53], off offset:48
	global_load_dwordx4 v[44:47], v[52:53], off offset:32
	global_load_dwordx4 v[48:51], v[52:53], off offset:16
	s_nop 0
	global_load_dwordx4 v[52:55], v[52:53], off
.LBB0_394:
	s_or_b64 exec, exec, s[24:25]
	s_add_u32 s2, s2, s94
	s_addc_u32 s3, s3, s34
	v_cmp_gt_i64_e32 vcc, s[2:3], v[192:193]
	s_cbranch_vccnz .Lmy_rsb_0_c2
	s_and_saveexec_b64 s[24:25], s[36:37]
	s_cbranch_execz .LBB0_397
	s_and_b32 s26, s2, 7
	s_lshl_b32 s26, s26, 3
	s_bfe_u32 s27, s2, 0x30003
	s_or_b32 s26, s26, s27
	s_mov_b32 s27, 0
	s_lshl_b64 s[26:27], s[26:27], 14
	v_lshl_add_u64 v[68:69], v[2:3], 0, s[26:27]
	global_load_dwordx4 v[56:59], v[68:69], off offset:48
	global_load_dwordx4 v[60:63], v[68:69], off offset:32
	global_load_dwordx4 v[64:67], v[68:69], off offset:16
	s_nop 0
	global_load_dwordx4 v[68:71], v[68:69], off
.LBB0_397:
	s_or_b64 exec, exec, s[24:25]
	s_add_u32 s2, s2, s94
	s_addc_u32 s3, s3, s34
	v_cmp_gt_i64_e32 vcc, s[2:3], v[192:193]
	s_cbranch_vccnz .Lmy_rsb_0_c3
	s_and_saveexec_b64 s[24:25], s[36:37]
	s_cbranch_execz .LBB0_400
	s_and_b32 s26, s2, 7
	s_lshl_b32 s26, s26, 3
	s_bfe_u32 s27, s2, 0x30003
	s_or_b32 s26, s26, s27
	s_mov_b32 s27, 0
	s_lshl_b64 s[26:27], s[26:27], 14
	v_lshl_add_u64 v[84:85], v[2:3], 0, s[26:27]
	global_load_dwordx4 v[72:75], v[84:85], off offset:48
	global_load_dwordx4 v[76:79], v[84:85], off offset:32
	global_load_dwordx4 v[80:83], v[84:85], off offset:16
	s_nop 0
	global_load_dwordx4 v[84:87], v[84:85], off
.LBB0_400:
	s_or_b64 exec, exec, s[24:25]
	s_add_u32 s2, s2, s94
	s_addc_u32 s3, s3, s34
	v_cmp_gt_i64_e32 vcc, s[2:3], v[192:193]
	s_cbranch_vccnz .Lmy_rsb_0_c4
	s_and_saveexec_b64 s[24:25], s[36:37]
	s_cbranch_execz .LBB0_403
	s_and_b32 s26, s2, 7
	s_lshl_b32 s26, s26, 3
	s_bfe_u32 s27, s2, 0x30003
	s_or_b32 s26, s26, s27
	s_mov_b32 s27, 0
	s_lshl_b64 s[26:27], s[26:27], 14
	v_lshl_add_u64 v[100:101], v[2:3], 0, s[26:27]
	global_load_dwordx4 v[88:91], v[100:101], off offset:48
	global_load_dwordx4 v[92:95], v[100:101], off offset:32
	global_load_dwordx4 v[96:99], v[100:101], off offset:16
	s_nop 0
	global_load_dwordx4 v[100:103], v[100:101], off
.LBB0_403:
	s_or_b64 exec, exec, s[24:25]
	s_add_u32 s2, s2, s94
	s_addc_u32 s3, s3, s34
	v_cmp_gt_i64_e32 vcc, s[2:3], v[192:193]
	s_cbranch_vccnz .Lmy_rsb_0_c5
	s_and_saveexec_b64 s[24:25], s[36:37]
	s_cbranch_execz .LBB0_406
	s_and_b32 s26, s2, 7
	s_lshl_b32 s26, s26, 3
	s_bfe_u32 s27, s2, 0x30003
	s_or_b32 s26, s26, s27
	s_mov_b32 s27, 0
	s_lshl_b64 s[26:27], s[26:27], 14
	v_lshl_add_u64 v[116:117], v[2:3], 0, s[26:27]
	global_load_dwordx4 v[104:107], v[116:117], off offset:48
	global_load_dwordx4 v[108:111], v[116:117], off offset:32
	global_load_dwordx4 v[112:115], v[116:117], off offset:16
	s_nop 0
	global_load_dwordx4 v[116:119], v[116:117], off
.LBB0_406:
	s_or_b64 exec, exec, s[24:25]
	s_add_u32 s2, s2, s94
	s_addc_u32 s3, s3, s34
	v_cmp_gt_i64_e32 vcc, s[2:3], v[192:193]
	s_cbranch_vccnz .Lmy_rsb_0_c6
	s_and_saveexec_b64 s[24:25], s[36:37]
	s_cbranch_execz .LBB0_409
	s_and_b32 s26, s2, 7
	s_lshl_b32 s26, s26, 3
	s_bfe_u32 s27, s2, 0x30003
	s_or_b32 s26, s26, s27
	s_mov_b32 s27, 0
	s_lshl_b64 s[26:27], s[26:27], 14
	v_lshl_add_u64 v[132:133], v[2:3], 0, s[26:27]
	global_load_dwordx4 v[120:123], v[132:133], off offset:48
	global_load_dwordx4 v[124:127], v[132:133], off offset:32
	global_load_dwordx4 v[128:131], v[132:133], off offset:16
	s_nop 0
	global_load_dwordx4 v[132:135], v[132:133], off
.LBB0_409:
	s_or_b64 exec, exec, s[24:25]
	s_add_u32 s2, s2, s94
	s_addc_u32 s3, s3, s34
	v_cmp_gt_i64_e32 vcc, s[2:3], v[192:193]
	s_cbranch_vccnz .Lmy_rsb_0_c7
	s_and_saveexec_b64 s[24:25], s[36:37]
	s_cbranch_execz .LBB0_412
	s_and_b32 s26, s2, 7
	s_lshl_b32 s26, s26, 3
	s_bfe_u32 s27, s2, 0x30003
	s_or_b32 s26, s26, s27
	s_mov_b32 s27, 0
	s_lshl_b64 s[26:27], s[26:27], 14
	v_lshl_add_u64 v[148:149], v[2:3], 0, s[26:27]
	global_load_dwordx4 v[136:139], v[148:149], off offset:48
	global_load_dwordx4 v[140:143], v[148:149], off offset:32
	global_load_dwordx4 v[144:147], v[148:149], off offset:16
	s_nop 0
	global_load_dwordx4 v[148:151], v[148:149], off
.LBB0_412:
	s_or_b64 exec, exec, s[24:25]
	s_add_u32 s2, s2, s94
	s_addc_u32 s3, s3, s34
	v_cmp_gt_i64_e32 vcc, s[2:3], v[192:193]
	s_cbranch_vccnz .Lmy_rsb_0_c8
	s_and_saveexec_b64 s[24:25], s[36:37]
	s_cbranch_execz .LBB0_415
	s_and_b32 s26, s2, 7
	s_lshl_b32 s26, s26, 3
	s_bfe_u32 s27, s2, 0x30003
	s_or_b32 s26, s26, s27
	s_mov_b32 s27, 0
	s_lshl_b64 s[26:27], s[26:27], 14
	v_lshl_add_u64 v[164:165], v[2:3], 0, s[26:27]
	global_load_dwordx4 v[152:155], v[164:165], off offset:48
	global_load_dwordx4 v[156:159], v[164:165], off offset:32
	global_load_dwordx4 v[160:163], v[164:165], off offset:16
	s_nop 0
	global_load_dwordx4 v[164:167], v[164:165], off
	s_or_b64 exec, exec, s[24:25]

;     __device__ bool next(int i, Unit& u) const { Unit b; if (!so.next(i >> 2, b)) return false; const int sub = i & 3; u.pm = b.pm; u.pn = sub * 4 + b.pn; u.acol = sub * 512; u.ord = i; return true; }
;     __device__ bool next(int i, Unit& u) const {
;         const long L = (long)i * G + c; if (L >= nwg) return false;
;         int wgid = (int)L; { const int q = nwg / NXCD, r = nwg % NXCD, xcd = wgid % NXCD, off = wgid / NXCD; wgid = (xcd < r ? xcd * (q + 1) : r * (q + 1) + (xcd - r) * q) + off; }
;         const int nig = WGM * nN, gid = wgid / nig, fm = gid * WGM, gsz = (nM - fm) < WGM ? (nM - fm) : WGM;
;         u.pm = fm + ((wgid % nig) % gsz); u.pn = (wgid % nig) / gsz; u.acol = 0; u.ord = i; return true;
; __device__ __forceinline__ float row_rstd(const float* rowsq, size_t row) {
;     const f32x4* q = (const f32x4*)(rowsq + row * 16); const f32x4 a = q[0], b = q[1], c = q[2], d = q[3];
.LBB0_415:
	s_or_b64 exec, exec, s[24:25]
	s_add_u32 s2, s2, s94
	s_addc_u32 s3, s3, s34
	v_cmp_gt_i64_e32 vcc, s[2:3], v[192:193]
	s_cbranch_vccnz .LBB0_424
	s_and_saveexec_b64 s[24:25], s[36:37]
	s_cbranch_execz .LBB0_418
	s_and_b32 s26, s2, 7
	s_lshl_b32 s26, s26, 3
	s_bfe_u32 s27, s2, 0x30003
	s_or_b32 s26, s26, s27
	s_mov_b32 s27, 0
	s_lshl_b64 s[26:27], s[26:27], 14
	v_lshl_add_u64 v[36:37], v[2:3], 0, s[26:27]
	global_load_dwordx4 v[24:27], v[36:37], off offset:48
	global_load_dwordx4 v[28:31], v[36:37], off offset:32
	global_load_dwordx4 v[32:35], v[36:37], off offset:16
	s_nop 0
	global_load_dwordx4 v[36:39], v[36:37], off
.LBB0_418:
	s_or_b64 exec, exec, s[24:25]
	s_add_u32 s2, s2, s94
	s_addc_u32 s3, s3, s34
	v_cmp_gt_i64_e32 vcc, s[2:3], v[192:193]
	s_cbranch_vccnz .Lmy_rsb_9_c1
	s_and_saveexec_b64 s[24:25], s[36:37]
	s_cbranch_execz .LBB0_421
	s_and_b32 s26, s2, 7
	s_lshl_b32 s26, s26, 3
	s_bfe_u32 s27, s2, 0x30003
	s_or_b32 s26, s26, s27
	s_mov_b32 s27, 0
	s_lshl_b64 s[26:27], s[26:27], 14
	v_lshl_add_u64 v[52:53], v[2:3], 0, s[26:27]
	global_load_dwordx4 v[40:43], v[52:53], off offset:48
	global_load_dwordx4 v[44:47], v[52:53], off offset:32
	global_load_dwordx4 v[48:51], v[52:53], off offset:16
	s_nop 0
	global_load_dwordx4 v[52:55], v[52:53], off
	s_or_b64 exec, exec, s[24:25]

;     __device__ bool next(int i, Unit& u) const { Unit b; if (!so.next(i >> 2, b)) return false; const int sub = i & 3; u.pm = b.pm; u.pn = sub * 4 + b.pn; u.acol = sub * 512; u.ord = i; return true; }
;     __device__ bool next(int i, Unit& u) const {
;         const long L = (long)i * G + c; if (L >= nwg) return false;
;         int wgid = (int)L; { const int q = nwg / NXCD, r = nwg % NXCD, xcd = wgid % NXCD, off = wgid / NXCD; wgid = (xcd < r ? xcd * (q + 1) : r * (q + 1) + (xcd - r) * q) + off; }
;         const int nig = WGM * nN, gid = wgid / nig, fm = gid * WGM, gsz = (nM - fm) < WGM ? (nM - fm) : WGM;
;         u.pm = fm + ((wgid % nig) % gsz); u.pn = (wgid % nig) / gsz; u.acol = 0; u.ord = i; return true;
; __device__ __forceinline__ float row_rstd(const float* rowsq, size_t row) {
;     const f32x4* q = (const f32x4*)(rowsq + row * 16); const f32x4 a = q[0], b = q[1], c = q[2], d = q[3];
.LBB0_2291:
	s_or_b64 exec, exec, s[0:1]
	v_readlane_b32 s0, v254, 5
	s_waitcnt lgkmcnt(0)
	s_barrier
	v_readlane_b32 s1, v254, 6
	s_ashr_i32 s34, s94, 31
	s_ashr_i32 s46, s71, 31
	v_writelane_b32 v254, s0, 5
	s_cmpk_lt_i32 s71, 0x580
	v_mov_b32_e32 v2, v216
	v_writelane_b32 v254, s1, 6
	s_cselect_b64 s[0:1], -1, 0
	s_cmpk_gt_i32 s71, 0x57f
	s_cbranch_scc1 .LBB0_2327
	v_readlane_b32 s2, v253, 37
	v_ashrrev_i32_e32 v3, 31, v2
	v_cmp_gt_i32_e64 s[36:37], s91, v2
	v_lshl_add_u32 v0, v2, 2, s2
	v_readlane_b32 s2, v251, 44
	v_lshlrev_b64 v[2:3], 6, v[2:3]
	v_readlane_b32 s3, v251, 45
	s_nop 1
	v_lshl_add_u64 v[2:3], s[2:3], 0, v[2:3]
	s_and_saveexec_b64 s[2:3], s[36:37]
	s_cbranch_execz .LBB0_2294
	s_and_b32 s24, s71, 7
	s_lshl_b32 s24, s24, 3
	s_bfe_u32 s25, s71, 0x30003
	s_or_b32 s24, s24, s25
	s_mov_b32 s25, 0
	s_lshl_b64 s[24:25], s[24:25], 14
	v_lshl_add_u64 v[36:37], v[2:3], 0, s[24:25]
	global_load_dwordx4 v[24:27], v[36:37], off offset:48
	global_load_dwordx4 v[28:31], v[36:37], off offset:32
	global_load_dwordx4 v[32:35], v[36:37], off offset:16
	s_nop 0
	global_load_dwordx4 v[36:39], v[36:37], off
.LBB0_2294:
	s_or_b64 exec, exec, s[2:3]
	s_add_u32 s2, s94, s71
	s_addc_u32 s3, s34, s46
	v_cmp_gt_i64_e32 vcc, s[2:3], v[184:185]
	s_cbranch_vccnz .Lmy_rsc_0_c1
	s_and_saveexec_b64 s[24:25], s[36:37]
	s_cbranch_execz .LBB0_2297
	s_and_b32 s26, s2, 7
	s_lshl_b32 s26, s26, 3
	s_bfe_u32 s27, s2, 0x30003
	s_or_b32 s26, s26, s27
	s_mov_b32 s27, 0
	s_lshl_b64 s[26:27], s[26:27], 14
	v_lshl_add_u64 v[52:53], v[2:3], 0, s[26:27]
	global_load_dwordx4 v[40:43], v[52:53], off offset:48
	global_load_dwordx4 v[44:47], v[52:53], off offset:32
	global_load_dwordx4 v[48:51], v[52:53], off offset:16
	s_nop 0
	global_load_dwordx4 v[52:55], v[52:53], off
.LBB0_2297:
	s_or_b64 exec, exec, s[24:25]
	s_add_u32 s2, s2, s94
	s_addc_u32 s3, s3, s34
	v_cmp_gt_i64_e32 vcc, s[2:3], v[184:185]
	s_cbranch_vccnz .Lmy_rsc_0_c2
	s_and_saveexec_b64 s[24:25], s[36:37]
	s_cbranch_execz .LBB0_2300
	s_and_b32 s26, s2, 7
	s_lshl_b32 s26, s26, 3
	s_bfe_u32 s27, s2, 0x30003
	s_or_b32 s26, s26, s27
	s_mov_b32 s27, 0
	s_lshl_b64 s[26:27], s[26:27], 14
	v_lshl_add_u64 v[68:69], v[2:3], 0, s[26:27]
	global_load_dwordx4 v[56:59], v[68:69], off offset:48
	global_load_dwordx4 v[60:63], v[68:69], off offset:32
	global_load_dwordx4 v[64:67], v[68:69], off offset:16
	s_nop 0
	global_load_dwordx4 v[68:71], v[68:69], off
.LBB0_2300:
	s_or_b64 exec, exec, s[24:25]
	s_add_u32 s2, s2, s94
	s_addc_u32 s3, s3, s34
	v_cmp_gt_i64_e32 vcc, s[2:3], v[184:185]
	s_cbranch_vccnz .Lmy_rsc_0_c3
	s_and_saveexec_b64 s[24:25], s[36:37]
	s_cbranch_execz .LBB0_2303
	s_and_b32 s26, s2, 7
	s_lshl_b32 s26, s26, 3
	s_bfe_u32 s27, s2, 0x30003
	s_or_b32 s26, s26, s27
	s_mov_b32 s27, 0
	s_lshl_b64 s[26:27], s[26:27], 14
	v_lshl_add_u64 v[84:85], v[2:3], 0, s[26:27]
	global_load_dwordx4 v[72:75], v[84:85], off offset:48
	global_load_dwordx4 v[76:79], v[84:85], off offset:32
	global_load_dwordx4 v[80:83], v[84:85], off offset:16
	s_nop 0
	global_load_dwordx4 v[84:87], v[84:85], off
.LBB0_2303:
	s_or_b64 exec, exec, s[24:25]
	s_add_u32 s2, s2, s94
	s_addc_u32 s3, s3, s34
	v_cmp_gt_i64_e32 vcc, s[2:3], v[184:185]
	s_cbranch_vccnz .Lmy_rsc_0_c4
	s_and_saveexec_b64 s[24:25], s[36:37]
	s_cbranch_execz .LBB0_2306
	s_and_b32 s26, s2, 7
	s_lshl_b32 s26, s26, 3
	s_bfe_u32 s27, s2, 0x30003
	s_or_b32 s26, s26, s27
	s_mov_b32 s27, 0
	s_lshl_b64 s[26:27], s[26:27], 14
	v_lshl_add_u64 v[100:101], v[2:3], 0, s[26:27]
	global_load_dwordx4 v[88:91], v[100:101], off offset:48
	global_load_dwordx4 v[92:95], v[100:101], off offset:32
	global_load_dwordx4 v[96:99], v[100:101], off offset:16
	s_nop 0
	global_load_dwordx4 v[100:103], v[100:101], off
.LBB0_2306:
	s_or_b64 exec, exec, s[24:25]
	s_add_u32 s2, s2, s94
	s_addc_u32 s3, s3, s34
	v_cmp_gt_i64_e32 vcc, s[2:3], v[184:185]
	s_cbranch_vccnz .Lmy_rsc_0_c5
	s_and_saveexec_b64 s[24:25], s[36:37]
	s_cbranch_execz .LBB0_2309
	s_and_b32 s26, s2, 7
	s_lshl_b32 s26, s26, 3
	s_bfe_u32 s27, s2, 0x30003
	s_or_b32 s26, s26, s27
	s_mov_b32 s27, 0
	s_lshl_b64 s[26:27], s[26:27], 14
	v_lshl_add_u64 v[116:117], v[2:3], 0, s[26:27]
	global_load_dwordx4 v[104:107], v[116:117], off offset:48
	global_load_dwordx4 v[108:111], v[116:117], off offset:32
	global_load_dwordx4 v[112:115], v[116:117], off offset:16
	s_nop 0
	global_load_dwordx4 v[116:119], v[116:117], off
	s_or_b64 exec, exec, s[24:25]
